# phase_mod inner loop rewritten by hand: 32 w_ada row loads in flight (double-buffered 16-row steps) instead of 4
# speedup vs baseline: 1.0099x; 1.0080x over previous
.LBB0_1326:
	s_mul_hi_i32 s1, s0, 0x2aaaaaab
	s_lshr_b32 s2, s1, 31
	s_ashr_i32 s1, s1, 4
	s_add_i32 s1, s1, s2
	s_mul_i32 s2, s1, 0x60
	s_sub_i32 s2, s0, s2
	s_lshl_b32 s2, s2, 6
	s_ashr_i32 s3, s2, 31
	s_mul_i32 s9, s1, 0x1800000
	s_lshl_b64 s[6:7], s[2:3], 2
	s_mul_hi_i32 s8, s1, 0x1800000
	s_add_u32 s2, s9, s6
	s_addc_u32 s3, s8, s7
	v_mov_b32_e32 v20, 0
	v_lshl_add_u64 v[18:19], v[16:17], 0, s[2:3]
	s_mov_b64 s[8:9], 0
	v_mov_b32_e32 v41, v38
	v_mov_b32_e32 v21, v20
	v_mov_b32_e32 v22, v20
	v_mov_b32_e32 v23, v20
	v_mov_b32_e32 v24, v20
	v_mov_b32_e32 v25, v20
	v_mov_b32_e32 v26, v20
	v_mov_b32_e32 v27, v20
	v_mov_b32_e32 v30, v20
	v_readfirstlane_b32 s10, v18
	v_readfirstlane_b32 s11, v19
	s_nop 1
	v_subrev_u32_e32 v62, s10, v18
	s_mov_b64 s[12:13], s[10:11]
	s_mov_b32 s8, 0
	global_load_dword v64, v62, s[12:13]
	s_add_u32 s12, s12, 0x6000
	s_addc_u32 s13, s13, 0
	global_load_dword v65, v62, s[12:13]
	s_add_u32 s12, s12, 0x6000
	s_addc_u32 s13, s13, 0
	global_load_dword v66, v62, s[12:13]
	s_add_u32 s12, s12, 0x6000
	s_addc_u32 s13, s13, 0
	global_load_dword v67, v62, s[12:13]
	s_add_u32 s12, s12, 0x6000
	s_addc_u32 s13, s13, 0
	global_load_dword v68, v62, s[12:13]
	s_add_u32 s12, s12, 0x6000
	s_addc_u32 s13, s13, 0
	global_load_dword v69, v62, s[12:13]
	s_add_u32 s12, s12, 0x6000
	s_addc_u32 s13, s13, 0
	global_load_dword v70, v62, s[12:13]
	s_add_u32 s12, s12, 0x6000
	s_addc_u32 s13, s13, 0
	global_load_dword v71, v62, s[12:13]
	s_add_u32 s12, s12, 0x6000
	s_addc_u32 s13, s13, 0
	global_load_dword v72, v62, s[12:13]
	s_add_u32 s12, s12, 0x6000
	s_addc_u32 s13, s13, 0
	global_load_dword v73, v62, s[12:13]
	s_add_u32 s12, s12, 0x6000
	s_addc_u32 s13, s13, 0
	global_load_dword v74, v62, s[12:13]
	s_add_u32 s12, s12, 0x6000
	s_addc_u32 s13, s13, 0
	global_load_dword v75, v62, s[12:13]
	s_add_u32 s12, s12, 0x6000
	s_addc_u32 s13, s13, 0
	global_load_dword v76, v62, s[12:13]
	s_add_u32 s12, s12, 0x6000
	s_addc_u32 s13, s13, 0
	global_load_dword v77, v62, s[12:13]
	s_add_u32 s12, s12, 0x6000
	s_addc_u32 s13, s13, 0
	global_load_dword v78, v62, s[12:13]
	s_add_u32 s12, s12, 0x6000
	s_addc_u32 s13, s13, 0
	global_load_dword v79, v62, s[12:13]
	s_add_u32 s12, s12, 0x6000
	s_addc_u32 s13, s13, 0
.Lmod_loop:
	global_load_dword v80, v62, s[12:13]
	s_add_u32 s12, s12, 0x6000
	s_addc_u32 s13, s13, 0
	global_load_dword v81, v62, s[12:13]
	s_add_u32 s12, s12, 0x6000
	s_addc_u32 s13, s13, 0
	global_load_dword v82, v62, s[12:13]
	s_add_u32 s12, s12, 0x6000
	s_addc_u32 s13, s13, 0
	global_load_dword v83, v62, s[12:13]
	s_add_u32 s12, s12, 0x6000
	s_addc_u32 s13, s13, 0
	global_load_dword v84, v62, s[12:13]
	s_add_u32 s12, s12, 0x6000
	s_addc_u32 s13, s13, 0
	global_load_dword v85, v62, s[12:13]
	s_add_u32 s12, s12, 0x6000
	s_addc_u32 s13, s13, 0
	global_load_dword v86, v62, s[12:13]
	s_add_u32 s12, s12, 0x6000
	s_addc_u32 s13, s13, 0
	global_load_dword v87, v62, s[12:13]
	s_add_u32 s12, s12, 0x6000
	s_addc_u32 s13, s13, 0
	global_load_dword v88, v62, s[12:13]
	s_add_u32 s12, s12, 0x6000
	s_addc_u32 s13, s13, 0
	global_load_dword v89, v62, s[12:13]
	s_add_u32 s12, s12, 0x6000
	s_addc_u32 s13, s13, 0
	global_load_dword v90, v62, s[12:13]
	s_add_u32 s12, s12, 0x6000
	s_addc_u32 s13, s13, 0
	global_load_dword v91, v62, s[12:13]
	s_add_u32 s12, s12, 0x6000
	s_addc_u32 s13, s13, 0
	global_load_dword v92, v62, s[12:13]
	s_add_u32 s12, s12, 0x6000
	s_addc_u32 s13, s13, 0
	global_load_dword v93, v62, s[12:13]
	s_add_u32 s12, s12, 0x6000
	s_addc_u32 s13, s13, 0
	global_load_dword v94, v62, s[12:13]
	s_add_u32 s12, s12, 0x6000
	s_addc_u32 s13, s13, 0
	global_load_dword v95, v62, s[12:13]
	s_add_u32 s12, s12, 0x6000
	s_addc_u32 s13, s13, 0
	s_waitcnt vmcnt(16)
	ds_read_b128 v[96:99], v41 offset:0
	ds_read_b128 v[100:103], v41 offset:4096
	ds_read_b128 v[104:107], v41 offset:8192
	ds_read_b128 v[108:111], v41 offset:12288
	ds_read_b128 v[112:115], v41 offset:16384
	ds_read_b128 v[116:119], v41 offset:20480
	ds_read_b128 v[120:123], v41 offset:24576
	ds_read_b128 v[124:127], v41 offset:28672
	ds_read_b128 v[128:131], v41 offset:32768
	s_waitcnt lgkmcnt(8)
	v_mul_f32_e32 v60, v65, v97
	v_fma_f32 v60, v64, v96, v60
	v_fma_f32 v60, v66, v98, v60
	v_fma_f32 v60, v67, v99, v60
	v_add_f32_e32 v20, v20, v60
	s_waitcnt lgkmcnt(7)
	v_mul_f32_e32 v60, v65, v101
	v_fma_f32 v60, v64, v100, v60
	v_fma_f32 v60, v66, v102, v60
	v_fma_f32 v60, v67, v103, v60
	v_add_f32_e32 v21, v21, v60
	s_waitcnt lgkmcnt(6)
	v_mul_f32_e32 v60, v65, v105
	v_fma_f32 v60, v64, v104, v60
	v_fma_f32 v60, v66, v106, v60
	v_fma_f32 v60, v67, v107, v60
	v_add_f32_e32 v22, v22, v60
	s_waitcnt lgkmcnt(5)
	v_mul_f32_e32 v60, v65, v109
	v_fma_f32 v60, v64, v108, v60
	v_fma_f32 v60, v66, v110, v60
	v_fma_f32 v60, v67, v111, v60
	v_add_f32_e32 v23, v23, v60
	s_waitcnt lgkmcnt(4)
	v_mul_f32_e32 v60, v65, v113
	v_fma_f32 v60, v64, v112, v60
	v_fma_f32 v60, v66, v114, v60
	v_fma_f32 v60, v67, v115, v60
	v_add_f32_e32 v24, v24, v60
	s_waitcnt lgkmcnt(3)
	v_mul_f32_e32 v60, v65, v117
	v_fma_f32 v60, v64, v116, v60
	v_fma_f32 v60, v66, v118, v60
	v_fma_f32 v60, v67, v119, v60
	v_add_f32_e32 v25, v25, v60
	s_waitcnt lgkmcnt(2)
	v_mul_f32_e32 v60, v65, v121
	v_fma_f32 v60, v64, v120, v60
	v_fma_f32 v60, v66, v122, v60
	v_fma_f32 v60, v67, v123, v60
	v_add_f32_e32 v26, v26, v60
	s_waitcnt lgkmcnt(1)
	v_mul_f32_e32 v60, v65, v125
	v_fma_f32 v60, v64, v124, v60
	v_fma_f32 v60, v66, v126, v60
	v_fma_f32 v60, v67, v127, v60
	v_add_f32_e32 v27, v27, v60
	s_waitcnt lgkmcnt(0)
	v_mul_f32_e32 v60, v64, v128
	v_mul_f32_e32 v61, v65, v129
	v_add_f32_e32 v60, v60, v61
	v_mul_f32_e32 v61, v66, v130
	v_add_f32_e32 v60, v61, v60
	v_mul_f32_e32 v61, v67, v131
	v_add_f32_e32 v60, v61, v60
	v_add_f32_e32 v30, v30, v60
	ds_read_b128 v[96:99], v41 offset:16
	ds_read_b128 v[100:103], v41 offset:4112
	ds_read_b128 v[104:107], v41 offset:8208
	ds_read_b128 v[108:111], v41 offset:12304
	ds_read_b128 v[112:115], v41 offset:16400
	ds_read_b128 v[116:119], v41 offset:20496
	ds_read_b128 v[120:123], v41 offset:24592
	ds_read_b128 v[124:127], v41 offset:28688
	ds_read_b128 v[128:131], v41 offset:32784
	s_waitcnt lgkmcnt(8)
	v_mul_f32_e32 v60, v69, v97
	v_fma_f32 v60, v68, v96, v60
	v_fma_f32 v60, v70, v98, v60
	v_fma_f32 v60, v71, v99, v60
	v_add_f32_e32 v20, v20, v60
	s_waitcnt lgkmcnt(7)
	v_mul_f32_e32 v60, v69, v101
	v_fma_f32 v60, v68, v100, v60
	v_fma_f32 v60, v70, v102, v60
	v_fma_f32 v60, v71, v103, v60
	v_add_f32_e32 v21, v21, v60
	s_waitcnt lgkmcnt(6)
	v_mul_f32_e32 v60, v69, v105
	v_fma_f32 v60, v68, v104, v60
	v_fma_f32 v60, v70, v106, v60
	v_fma_f32 v60, v71, v107, v60
	v_add_f32_e32 v22, v22, v60
	s_waitcnt lgkmcnt(5)
	v_mul_f32_e32 v60, v69, v109
	v_fma_f32 v60, v68, v108, v60
	v_fma_f32 v60, v70, v110, v60
	v_fma_f32 v60, v71, v111, v60
	v_add_f32_e32 v23, v23, v60
	s_waitcnt lgkmcnt(4)
	v_mul_f32_e32 v60, v69, v113
	v_fma_f32 v60, v68, v112, v60
	v_fma_f32 v60, v70, v114, v60
	v_fma_f32 v60, v71, v115, v60
	v_add_f32_e32 v24, v24, v60
	s_waitcnt lgkmcnt(3)
	v_mul_f32_e32 v60, v69, v117
	v_fma_f32 v60, v68, v116, v60
	v_fma_f32 v60, v70, v118, v60
	v_fma_f32 v60, v71, v119, v60
	v_add_f32_e32 v25, v25, v60
	s_waitcnt lgkmcnt(2)
	v_mul_f32_e32 v60, v69, v121
	v_fma_f32 v60, v68, v120, v60
	v_fma_f32 v60, v70, v122, v60
	v_fma_f32 v60, v71, v123, v60
	v_add_f32_e32 v26, v26, v60
	s_waitcnt lgkmcnt(1)
	v_mul_f32_e32 v60, v69, v125
	v_fma_f32 v60, v68, v124, v60
	v_fma_f32 v60, v70, v126, v60
	v_fma_f32 v60, v71, v127, v60
	v_add_f32_e32 v27, v27, v60
	s_waitcnt lgkmcnt(0)
	v_mul_f32_e32 v60, v68, v128
	v_mul_f32_e32 v61, v69, v129
	v_add_f32_e32 v60, v60, v61
	v_mul_f32_e32 v61, v70, v130
	v_add_f32_e32 v60, v61, v60
	v_mul_f32_e32 v61, v71, v131
	v_add_f32_e32 v60, v61, v60
	v_add_f32_e32 v30, v30, v60
	ds_read_b128 v[96:99], v41 offset:32
	ds_read_b128 v[100:103], v41 offset:4128
	ds_read_b128 v[104:107], v41 offset:8224
	ds_read_b128 v[108:111], v41 offset:12320
	ds_read_b128 v[112:115], v41 offset:16416
	ds_read_b128 v[116:119], v41 offset:20512
	ds_read_b128 v[120:123], v41 offset:24608
	ds_read_b128 v[124:127], v41 offset:28704
	ds_read_b128 v[128:131], v41 offset:32800
	s_waitcnt lgkmcnt(8)
	v_mul_f32_e32 v60, v73, v97
	v_fma_f32 v60, v72, v96, v60
	v_fma_f32 v60, v74, v98, v60
	v_fma_f32 v60, v75, v99, v60
	v_add_f32_e32 v20, v20, v60
	s_waitcnt lgkmcnt(7)
	v_mul_f32_e32 v60, v73, v101
	v_fma_f32 v60, v72, v100, v60
	v_fma_f32 v60, v74, v102, v60
	v_fma_f32 v60, v75, v103, v60
	v_add_f32_e32 v21, v21, v60
	s_waitcnt lgkmcnt(6)
	v_mul_f32_e32 v60, v73, v105
	v_fma_f32 v60, v72, v104, v60
	v_fma_f32 v60, v74, v106, v60
	v_fma_f32 v60, v75, v107, v60
	v_add_f32_e32 v22, v22, v60
	s_waitcnt lgkmcnt(5)
	v_mul_f32_e32 v60, v73, v109
	v_fma_f32 v60, v72, v108, v60
	v_fma_f32 v60, v74, v110, v60
	v_fma_f32 v60, v75, v111, v60
	v_add_f32_e32 v23, v23, v60
	s_waitcnt lgkmcnt(4)
	v_mul_f32_e32 v60, v73, v113
	v_fma_f32 v60, v72, v112, v60
	v_fma_f32 v60, v74, v114, v60
	v_fma_f32 v60, v75, v115, v60
	v_add_f32_e32 v24, v24, v60
	s_waitcnt lgkmcnt(3)
	v_mul_f32_e32 v60, v73, v117
	v_fma_f32 v60, v72, v116, v60
	v_fma_f32 v60, v74, v118, v60
	v_fma_f32 v60, v75, v119, v60
	v_add_f32_e32 v25, v25, v60
	s_waitcnt lgkmcnt(2)
	v_mul_f32_e32 v60, v73, v121
	v_fma_f32 v60, v72, v120, v60
	v_fma_f32 v60, v74, v122, v60
	v_fma_f32 v60, v75, v123, v60
	v_add_f32_e32 v26, v26, v60
	s_waitcnt lgkmcnt(1)
	v_mul_f32_e32 v60, v73, v125
	v_fma_f32 v60, v72, v124, v60
	v_fma_f32 v60, v74, v126, v60
	v_fma_f32 v60, v75, v127, v60
	v_add_f32_e32 v27, v27, v60
	s_waitcnt lgkmcnt(0)
	v_mul_f32_e32 v60, v72, v128
	v_mul_f32_e32 v61, v73, v129
	v_add_f32_e32 v60, v60, v61
	v_mul_f32_e32 v61, v74, v130
	v_add_f32_e32 v60, v61, v60
	v_mul_f32_e32 v61, v75, v131
	v_add_f32_e32 v60, v61, v60
	v_add_f32_e32 v30, v30, v60
	ds_read_b128 v[96:99], v41 offset:48
	ds_read_b128 v[100:103], v41 offset:4144
	ds_read_b128 v[104:107], v41 offset:8240
	ds_read_b128 v[108:111], v41 offset:12336
	ds_read_b128 v[112:115], v41 offset:16432
	ds_read_b128 v[116:119], v41 offset:20528
	ds_read_b128 v[120:123], v41 offset:24624
	ds_read_b128 v[124:127], v41 offset:28720
	ds_read_b128 v[128:131], v41 offset:32816
	s_waitcnt lgkmcnt(8)
	v_mul_f32_e32 v60, v77, v97
	v_fma_f32 v60, v76, v96, v60
	v_fma_f32 v60, v78, v98, v60
	v_fma_f32 v60, v79, v99, v60
	v_add_f32_e32 v20, v20, v60
	s_waitcnt lgkmcnt(7)
	v_mul_f32_e32 v60, v77, v101
	v_fma_f32 v60, v76, v100, v60
	v_fma_f32 v60, v78, v102, v60
	v_fma_f32 v60, v79, v103, v60
	v_add_f32_e32 v21, v21, v60
	s_waitcnt lgkmcnt(6)
	v_mul_f32_e32 v60, v77, v105
	v_fma_f32 v60, v76, v104, v60
	v_fma_f32 v60, v78, v106, v60
	v_fma_f32 v60, v79, v107, v60
	v_add_f32_e32 v22, v22, v60
	s_waitcnt lgkmcnt(5)
	v_mul_f32_e32 v60, v77, v109
	v_fma_f32 v60, v76, v108, v60
	v_fma_f32 v60, v78, v110, v60
	v_fma_f32 v60, v79, v111, v60
	v_add_f32_e32 v23, v23, v60
	s_waitcnt lgkmcnt(4)
	v_mul_f32_e32 v60, v77, v113
	v_fma_f32 v60, v76, v112, v60
	v_fma_f32 v60, v78, v114, v60
	v_fma_f32 v60, v79, v115, v60
	v_add_f32_e32 v24, v24, v60
	s_waitcnt lgkmcnt(3)
	v_mul_f32_e32 v60, v77, v117
	v_fma_f32 v60, v76, v116, v60
	v_fma_f32 v60, v78, v118, v60
	v_fma_f32 v60, v79, v119, v60
	v_add_f32_e32 v25, v25, v60
	s_waitcnt lgkmcnt(2)
	v_mul_f32_e32 v60, v77, v121
	v_fma_f32 v60, v76, v120, v60
	v_fma_f32 v60, v78, v122, v60
	v_fma_f32 v60, v79, v123, v60
	v_add_f32_e32 v26, v26, v60
	s_waitcnt lgkmcnt(1)
	v_mul_f32_e32 v60, v77, v125
	v_fma_f32 v60, v76, v124, v60
	v_fma_f32 v60, v78, v126, v60
	v_fma_f32 v60, v79, v127, v60
	v_add_f32_e32 v27, v27, v60
	s_waitcnt lgkmcnt(0)
	v_mul_f32_e32 v60, v76, v128
	v_mul_f32_e32 v61, v77, v129
	v_add_f32_e32 v60, v60, v61
	v_mul_f32_e32 v61, v78, v130
	v_add_f32_e32 v60, v61, v60
	v_mul_f32_e32 v61, v79, v131
	v_add_f32_e32 v60, v61, v60
	v_add_f32_e32 v30, v30, v60
	v_add_u32_e32 v41, 64, v41
	s_cmp_eq_u32 s8, 6
	s_cbranch_scc1 .Lmod_last
	global_load_dword v64, v62, s[12:13]
	s_add_u32 s12, s12, 0x6000
	s_addc_u32 s13, s13, 0
	global_load_dword v65, v62, s[12:13]
	s_add_u32 s12, s12, 0x6000
	s_addc_u32 s13, s13, 0
	global_load_dword v66, v62, s[12:13]
	s_add_u32 s12, s12, 0x6000
	s_addc_u32 s13, s13, 0
	global_load_dword v67, v62, s[12:13]
	s_add_u32 s12, s12, 0x6000
	s_addc_u32 s13, s13, 0
	global_load_dword v68, v62, s[12:13]
	s_add_u32 s12, s12, 0x6000
	s_addc_u32 s13, s13, 0
	global_load_dword v69, v62, s[12:13]
	s_add_u32 s12, s12, 0x6000
	s_addc_u32 s13, s13, 0
	global_load_dword v70, v62, s[12:13]
	s_add_u32 s12, s12, 0x6000
	s_addc_u32 s13, s13, 0
	global_load_dword v71, v62, s[12:13]
	s_add_u32 s12, s12, 0x6000
	s_addc_u32 s13, s13, 0
	global_load_dword v72, v62, s[12:13]
	s_add_u32 s12, s12, 0x6000
	s_addc_u32 s13, s13, 0
	global_load_dword v73, v62, s[12:13]
	s_add_u32 s12, s12, 0x6000
	s_addc_u32 s13, s13, 0
	global_load_dword v74, v62, s[12:13]
	s_add_u32 s12, s12, 0x6000
	s_addc_u32 s13, s13, 0
	global_load_dword v75, v62, s[12:13]
	s_add_u32 s12, s12, 0x6000
	s_addc_u32 s13, s13, 0
	global_load_dword v76, v62, s[12:13]
	s_add_u32 s12, s12, 0x6000
	s_addc_u32 s13, s13, 0
	global_load_dword v77, v62, s[12:13]
	s_add_u32 s12, s12, 0x6000
	s_addc_u32 s13, s13, 0
	global_load_dword v78, v62, s[12:13]
	s_add_u32 s12, s12, 0x6000
	s_addc_u32 s13, s13, 0
	global_load_dword v79, v62, s[12:13]
	s_add_u32 s12, s12, 0x6000
	s_addc_u32 s13, s13, 0
	s_waitcnt vmcnt(16)
	ds_read_b128 v[96:99], v41 offset:0
	ds_read_b128 v[100:103], v41 offset:4096
	ds_read_b128 v[104:107], v41 offset:8192
	ds_read_b128 v[108:111], v41 offset:12288
	ds_read_b128 v[112:115], v41 offset:16384
	ds_read_b128 v[116:119], v41 offset:20480
	ds_read_b128 v[120:123], v41 offset:24576
	ds_read_b128 v[124:127], v41 offset:28672
	ds_read_b128 v[128:131], v41 offset:32768
	s_waitcnt lgkmcnt(8)
	v_mul_f32_e32 v60, v81, v97
	v_fma_f32 v60, v80, v96, v60
	v_fma_f32 v60, v82, v98, v60
	v_fma_f32 v60, v83, v99, v60
	v_add_f32_e32 v20, v20, v60
	s_waitcnt lgkmcnt(7)
	v_mul_f32_e32 v60, v81, v101
	v_fma_f32 v60, v80, v100, v60
	v_fma_f32 v60, v82, v102, v60
	v_fma_f32 v60, v83, v103, v60
	v_add_f32_e32 v21, v21, v60
	s_waitcnt lgkmcnt(6)
	v_mul_f32_e32 v60, v81, v105
	v_fma_f32 v60, v80, v104, v60
	v_fma_f32 v60, v82, v106, v60
	v_fma_f32 v60, v83, v107, v60
	v_add_f32_e32 v22, v22, v60
	s_waitcnt lgkmcnt(5)
	v_mul_f32_e32 v60, v81, v109
	v_fma_f32 v60, v80, v108, v60
	v_fma_f32 v60, v82, v110, v60
	v_fma_f32 v60, v83, v111, v60
	v_add_f32_e32 v23, v23, v60
	s_waitcnt lgkmcnt(4)
	v_mul_f32_e32 v60, v81, v113
	v_fma_f32 v60, v80, v112, v60
	v_fma_f32 v60, v82, v114, v60
	v_fma_f32 v60, v83, v115, v60
	v_add_f32_e32 v24, v24, v60
	s_waitcnt lgkmcnt(3)
	v_mul_f32_e32 v60, v81, v117
	v_fma_f32 v60, v80, v116, v60
	v_fma_f32 v60, v82, v118, v60
	v_fma_f32 v60, v83, v119, v60
	v_add_f32_e32 v25, v25, v60
	s_waitcnt lgkmcnt(2)
	v_mul_f32_e32 v60, v81, v121
	v_fma_f32 v60, v80, v120, v60
	v_fma_f32 v60, v82, v122, v60
	v_fma_f32 v60, v83, v123, v60
	v_add_f32_e32 v26, v26, v60
	s_waitcnt lgkmcnt(1)
	v_mul_f32_e32 v60, v81, v125
	v_fma_f32 v60, v80, v124, v60
	v_fma_f32 v60, v82, v126, v60
	v_fma_f32 v60, v83, v127, v60
	v_add_f32_e32 v27, v27, v60
	s_waitcnt lgkmcnt(0)
	v_mul_f32_e32 v60, v80, v128
	v_mul_f32_e32 v61, v81, v129
	v_add_f32_e32 v60, v60, v61
	v_mul_f32_e32 v61, v82, v130
	v_add_f32_e32 v60, v61, v60
	v_mul_f32_e32 v61, v83, v131
	v_add_f32_e32 v60, v61, v60
	v_add_f32_e32 v30, v30, v60
	ds_read_b128 v[96:99], v41 offset:16
	ds_read_b128 v[100:103], v41 offset:4112
	ds_read_b128 v[104:107], v41 offset:8208
	ds_read_b128 v[108:111], v41 offset:12304
	ds_read_b128 v[112:115], v41 offset:16400
	ds_read_b128 v[116:119], v41 offset:20496
	ds_read_b128 v[120:123], v41 offset:24592
	ds_read_b128 v[124:127], v41 offset:28688
	ds_read_b128 v[128:131], v41 offset:32784
	s_waitcnt lgkmcnt(8)
	v_mul_f32_e32 v60, v85, v97
	v_fma_f32 v60, v84, v96, v60
	v_fma_f32 v60, v86, v98, v60
	v_fma_f32 v60, v87, v99, v60
	v_add_f32_e32 v20, v20, v60
	s_waitcnt lgkmcnt(7)
	v_mul_f32_e32 v60, v85, v101
	v_fma_f32 v60, v84, v100, v60
	v_fma_f32 v60, v86, v102, v60
	v_fma_f32 v60, v87, v103, v60
	v_add_f32_e32 v21, v21, v60
	s_waitcnt lgkmcnt(6)
	v_mul_f32_e32 v60, v85, v105
	v_fma_f32 v60, v84, v104, v60
	v_fma_f32 v60, v86, v106, v60
	v_fma_f32 v60, v87, v107, v60
	v_add_f32_e32 v22, v22, v60
	s_waitcnt lgkmcnt(5)
	v_mul_f32_e32 v60, v85, v109
	v_fma_f32 v60, v84, v108, v60
	v_fma_f32 v60, v86, v110, v60
	v_fma_f32 v60, v87, v111, v60
	v_add_f32_e32 v23, v23, v60
	s_waitcnt lgkmcnt(4)
	v_mul_f32_e32 v60, v85, v113
	v_fma_f32 v60, v84, v112, v60
	v_fma_f32 v60, v86, v114, v60
	v_fma_f32 v60, v87, v115, v60
	v_add_f32_e32 v24, v24, v60
	s_waitcnt lgkmcnt(3)
	v_mul_f32_e32 v60, v85, v117
	v_fma_f32 v60, v84, v116, v60
	v_fma_f32 v60, v86, v118, v60
	v_fma_f32 v60, v87, v119, v60
	v_add_f32_e32 v25, v25, v60
	s_waitcnt lgkmcnt(2)
	v_mul_f32_e32 v60, v85, v121
	v_fma_f32 v60, v84, v120, v60
	v_fma_f32 v60, v86, v122, v60
	v_fma_f32 v60, v87, v123, v60
	v_add_f32_e32 v26, v26, v60
	s_waitcnt lgkmcnt(1)
	v_mul_f32_e32 v60, v85, v125
	v_fma_f32 v60, v84, v124, v60
	v_fma_f32 v60, v86, v126, v60
	v_fma_f32 v60, v87, v127, v60
	v_add_f32_e32 v27, v27, v60
	s_waitcnt lgkmcnt(0)
	v_mul_f32_e32 v60, v84, v128
	v_mul_f32_e32 v61, v85, v129
	v_add_f32_e32 v60, v60, v61
	v_mul_f32_e32 v61, v86, v130
	v_add_f32_e32 v60, v61, v60
	v_mul_f32_e32 v61, v87, v131
	v_add_f32_e32 v60, v61, v60
	v_add_f32_e32 v30, v30, v60
	ds_read_b128 v[96:99], v41 offset:32
	ds_read_b128 v[100:103], v41 offset:4128
	ds_read_b128 v[104:107], v41 offset:8224
	ds_read_b128 v[108:111], v41 offset:12320
	ds_read_b128 v[112:115], v41 offset:16416
	ds_read_b128 v[116:119], v41 offset:20512
	ds_read_b128 v[120:123], v41 offset:24608
	ds_read_b128 v[124:127], v41 offset:28704
	ds_read_b128 v[128:131], v41 offset:32800
	s_waitcnt lgkmcnt(8)
	v_mul_f32_e32 v60, v89, v97
	v_fma_f32 v60, v88, v96, v60
	v_fma_f32 v60, v90, v98, v60
	v_fma_f32 v60, v91, v99, v60
	v_add_f32_e32 v20, v20, v60
	s_waitcnt lgkmcnt(7)
	v_mul_f32_e32 v60, v89, v101
	v_fma_f32 v60, v88, v100, v60
	v_fma_f32 v60, v90, v102, v60
	v_fma_f32 v60, v91, v103, v60
	v_add_f32_e32 v21, v21, v60
	s_waitcnt lgkmcnt(6)
	v_mul_f32_e32 v60, v89, v105
	v_fma_f32 v60, v88, v104, v60
	v_fma_f32 v60, v90, v106, v60
	v_fma_f32 v60, v91, v107, v60
	v_add_f32_e32 v22, v22, v60
	s_waitcnt lgkmcnt(5)
	v_mul_f32_e32 v60, v89, v109
	v_fma_f32 v60, v88, v108, v60
	v_fma_f32 v60, v90, v110, v60
	v_fma_f32 v60, v91, v111, v60
	v_add_f32_e32 v23, v23, v60
	s_waitcnt lgkmcnt(4)
	v_mul_f32_e32 v60, v89, v113
	v_fma_f32 v60, v88, v112, v60
	v_fma_f32 v60, v90, v114, v60
	v_fma_f32 v60, v91, v115, v60
	v_add_f32_e32 v24, v24, v60
	s_waitcnt lgkmcnt(3)
	v_mul_f32_e32 v60, v89, v117
	v_fma_f32 v60, v88, v116, v60
	v_fma_f32 v60, v90, v118, v60
	v_fma_f32 v60, v91, v119, v60
	v_add_f32_e32 v25, v25, v60
	s_waitcnt lgkmcnt(2)
	v_mul_f32_e32 v60, v89, v121
	v_fma_f32 v60, v88, v120, v60
	v_fma_f32 v60, v90, v122, v60
	v_fma_f32 v60, v91, v123, v60
	v_add_f32_e32 v26, v26, v60
	s_waitcnt lgkmcnt(1)
	v_mul_f32_e32 v60, v89, v125
	v_fma_f32 v60, v88, v124, v60
	v_fma_f32 v60, v90, v126, v60
	v_fma_f32 v60, v91, v127, v60
	v_add_f32_e32 v27, v27, v60
	s_waitcnt lgkmcnt(0)
	v_mul_f32_e32 v60, v88, v128
	v_mul_f32_e32 v61, v89, v129
	v_add_f32_e32 v60, v60, v61
	v_mul_f32_e32 v61, v90, v130
	v_add_f32_e32 v60, v61, v60
	v_mul_f32_e32 v61, v91, v131
	v_add_f32_e32 v60, v61, v60
	v_add_f32_e32 v30, v30, v60
	ds_read_b128 v[96:99], v41 offset:48
	ds_read_b128 v[100:103], v41 offset:4144
	ds_read_b128 v[104:107], v41 offset:8240
	ds_read_b128 v[108:111], v41 offset:12336
	ds_read_b128 v[112:115], v41 offset:16432
	ds_read_b128 v[116:119], v41 offset:20528
	ds_read_b128 v[120:123], v41 offset:24624
	ds_read_b128 v[124:127], v41 offset:28720
	ds_read_b128 v[128:131], v41 offset:32816
	s_waitcnt lgkmcnt(8)
	v_mul_f32_e32 v60, v93, v97
	v_fma_f32 v60, v92, v96, v60
	v_fma_f32 v60, v94, v98, v60
	v_fma_f32 v60, v95, v99, v60
	v_add_f32_e32 v20, v20, v60
	s_waitcnt lgkmcnt(7)
	v_mul_f32_e32 v60, v93, v101
	v_fma_f32 v60, v92, v100, v60
	v_fma_f32 v60, v94, v102, v60
	v_fma_f32 v60, v95, v103, v60
	v_add_f32_e32 v21, v21, v60
	s_waitcnt lgkmcnt(6)
	v_mul_f32_e32 v60, v93, v105
	v_fma_f32 v60, v92, v104, v60
	v_fma_f32 v60, v94, v106, v60
	v_fma_f32 v60, v95, v107, v60
	v_add_f32_e32 v22, v22, v60
	s_waitcnt lgkmcnt(5)
	v_mul_f32_e32 v60, v93, v109
	v_fma_f32 v60, v92, v108, v60
	v_fma_f32 v60, v94, v110, v60
	v_fma_f32 v60, v95, v111, v60
	v_add_f32_e32 v23, v23, v60
	s_waitcnt lgkmcnt(4)
	v_mul_f32_e32 v60, v93, v113
	v_fma_f32 v60, v92, v112, v60
	v_fma_f32 v60, v94, v114, v60
	v_fma_f32 v60, v95, v115, v60
	v_add_f32_e32 v24, v24, v60
	s_waitcnt lgkmcnt(3)
	v_mul_f32_e32 v60, v93, v117
	v_fma_f32 v60, v92, v116, v60
	v_fma_f32 v60, v94, v118, v60
	v_fma_f32 v60, v95, v119, v60
	v_add_f32_e32 v25, v25, v60
	s_waitcnt lgkmcnt(2)
	v_mul_f32_e32 v60, v93, v121
	v_fma_f32 v60, v92, v120, v60
	v_fma_f32 v60, v94, v122, v60
	v_fma_f32 v60, v95, v123, v60
	v_add_f32_e32 v26, v26, v60
	s_waitcnt lgkmcnt(1)
	v_mul_f32_e32 v60, v93, v125
	v_fma_f32 v60, v92, v124, v60
	v_fma_f32 v60, v94, v126, v60
	v_fma_f32 v60, v95, v127, v60
	v_add_f32_e32 v27, v27, v60
	s_waitcnt lgkmcnt(0)
	v_mul_f32_e32 v60, v92, v128
	v_mul_f32_e32 v61, v93, v129
	v_add_f32_e32 v60, v60, v61
	v_mul_f32_e32 v61, v94, v130
	v_add_f32_e32 v60, v61, v60
	v_mul_f32_e32 v61, v95, v131
	v_add_f32_e32 v60, v61, v60
	v_add_f32_e32 v30, v30, v60
	v_add_u32_e32 v41, 64, v41
	s_add_i32 s8, s8, 2
	s_branch .Lmod_loop
.Lmod_last:
	s_waitcnt vmcnt(0)
	ds_read_b128 v[96:99], v41 offset:0
	ds_read_b128 v[100:103], v41 offset:4096
	ds_read_b128 v[104:107], v41 offset:8192
	ds_read_b128 v[108:111], v41 offset:12288
	ds_read_b128 v[112:115], v41 offset:16384
	ds_read_b128 v[116:119], v41 offset:20480
	ds_read_b128 v[120:123], v41 offset:24576
	ds_read_b128 v[124:127], v41 offset:28672
	ds_read_b128 v[128:131], v41 offset:32768
	s_waitcnt lgkmcnt(8)
	v_mul_f32_e32 v60, v81, v97
	v_fma_f32 v60, v80, v96, v60
	v_fma_f32 v60, v82, v98, v60
	v_fma_f32 v60, v83, v99, v60
	v_add_f32_e32 v20, v20, v60
	s_waitcnt lgkmcnt(7)
	v_mul_f32_e32 v60, v81, v101
	v_fma_f32 v60, v80, v100, v60
	v_fma_f32 v60, v82, v102, v60
	v_fma_f32 v60, v83, v103, v60
	v_add_f32_e32 v21, v21, v60
	s_waitcnt lgkmcnt(6)
	v_mul_f32_e32 v60, v81, v105
	v_fma_f32 v60, v80, v104, v60
	v_fma_f32 v60, v82, v106, v60
	v_fma_f32 v60, v83, v107, v60
	v_add_f32_e32 v22, v22, v60
	s_waitcnt lgkmcnt(5)
	v_mul_f32_e32 v60, v81, v109
	v_fma_f32 v60, v80, v108, v60
	v_fma_f32 v60, v82, v110, v60
	v_fma_f32 v60, v83, v111, v60
	v_add_f32_e32 v23, v23, v60
	s_waitcnt lgkmcnt(4)
	v_mul_f32_e32 v60, v81, v113
	v_fma_f32 v60, v80, v112, v60
	v_fma_f32 v60, v82, v114, v60
	v_fma_f32 v60, v83, v115, v60
	v_add_f32_e32 v24, v24, v60
	s_waitcnt lgkmcnt(3)
	v_mul_f32_e32 v60, v81, v117
	v_fma_f32 v60, v80, v116, v60
	v_fma_f32 v60, v82, v118, v60
	v_fma_f32 v60, v83, v119, v60
	v_add_f32_e32 v25, v25, v60
	s_waitcnt lgkmcnt(2)
	v_mul_f32_e32 v60, v81, v121
	v_fma_f32 v60, v80, v120, v60
	v_fma_f32 v60, v82, v122, v60
	v_fma_f32 v60, v83, v123, v60
	v_add_f32_e32 v26, v26, v60
	s_waitcnt lgkmcnt(1)
	v_mul_f32_e32 v60, v81, v125
	v_fma_f32 v60, v80, v124, v60
	v_fma_f32 v60, v82, v126, v60
	v_fma_f32 v60, v83, v127, v60
	v_add_f32_e32 v27, v27, v60
	s_waitcnt lgkmcnt(0)
	v_mul_f32_e32 v60, v80, v128
	v_mul_f32_e32 v61, v81, v129
	v_add_f32_e32 v60, v60, v61
	v_mul_f32_e32 v61, v82, v130
	v_add_f32_e32 v60, v61, v60
	v_mul_f32_e32 v61, v83, v131
	v_add_f32_e32 v60, v61, v60
	v_add_f32_e32 v30, v30, v60
	ds_read_b128 v[96:99], v41 offset:16
	ds_read_b128 v[100:103], v41 offset:4112
	ds_read_b128 v[104:107], v41 offset:8208
	ds_read_b128 v[108:111], v41 offset:12304
	ds_read_b128 v[112:115], v41 offset:16400
	ds_read_b128 v[116:119], v41 offset:20496
	ds_read_b128 v[120:123], v41 offset:24592
	ds_read_b128 v[124:127], v41 offset:28688
	ds_read_b128 v[128:131], v41 offset:32784
	s_waitcnt lgkmcnt(8)
	v_mul_f32_e32 v60, v85, v97
	v_fma_f32 v60, v84, v96, v60
	v_fma_f32 v60, v86, v98, v60
	v_fma_f32 v60, v87, v99, v60
	v_add_f32_e32 v20, v20, v60
	s_waitcnt lgkmcnt(7)
	v_mul_f32_e32 v60, v85, v101
	v_fma_f32 v60, v84, v100, v60
	v_fma_f32 v60, v86, v102, v60
	v_fma_f32 v60, v87, v103, v60
	v_add_f32_e32 v21, v21, v60
	s_waitcnt lgkmcnt(6)
	v_mul_f32_e32 v60, v85, v105
	v_fma_f32 v60, v84, v104, v60
	v_fma_f32 v60, v86, v106, v60
	v_fma_f32 v60, v87, v107, v60
	v_add_f32_e32 v22, v22, v60
	s_waitcnt lgkmcnt(5)
	v_mul_f32_e32 v60, v85, v109
	v_fma_f32 v60, v84, v108, v60
	v_fma_f32 v60, v86, v110, v60
	v_fma_f32 v60, v87, v111, v60
	v_add_f32_e32 v23, v23, v60
	s_waitcnt lgkmcnt(4)
	v_mul_f32_e32 v60, v85, v113
	v_fma_f32 v60, v84, v112, v60
	v_fma_f32 v60, v86, v114, v60
	v_fma_f32 v60, v87, v115, v60
	v_add_f32_e32 v24, v24, v60
	s_waitcnt lgkmcnt(3)
	v_mul_f32_e32 v60, v85, v117
	v_fma_f32 v60, v84, v116, v60
	v_fma_f32 v60, v86, v118, v60
	v_fma_f32 v60, v87, v119, v60
	v_add_f32_e32 v25, v25, v60
	s_waitcnt lgkmcnt(2)
	v_mul_f32_e32 v60, v85, v121
	v_fma_f32 v60, v84, v120, v60
	v_fma_f32 v60, v86, v122, v60
	v_fma_f32 v60, v87, v123, v60
	v_add_f32_e32 v26, v26, v60
	s_waitcnt lgkmcnt(1)
	v_mul_f32_e32 v60, v85, v125
	v_fma_f32 v60, v84, v124, v60
	v_fma_f32 v60, v86, v126, v60
	v_fma_f32 v60, v87, v127, v60
	v_add_f32_e32 v27, v27, v60
	s_waitcnt lgkmcnt(0)
	v_mul_f32_e32 v60, v84, v128
	v_mul_f32_e32 v61, v85, v129
	v_add_f32_e32 v60, v60, v61
	v_mul_f32_e32 v61, v86, v130
	v_add_f32_e32 v60, v61, v60
	v_mul_f32_e32 v61, v87, v131
	v_add_f32_e32 v60, v61, v60
	v_add_f32_e32 v30, v30, v60
	ds_read_b128 v[96:99], v41 offset:32
	ds_read_b128 v[100:103], v41 offset:4128
	ds_read_b128 v[104:107], v41 offset:8224
	ds_read_b128 v[108:111], v41 offset:12320
	ds_read_b128 v[112:115], v41 offset:16416
	ds_read_b128 v[116:119], v41 offset:20512
	ds_read_b128 v[120:123], v41 offset:24608
	ds_read_b128 v[124:127], v41 offset:28704
	ds_read_b128 v[128:131], v41 offset:32800
	s_waitcnt lgkmcnt(8)
	v_mul_f32_e32 v60, v89, v97
	v_fma_f32 v60, v88, v96, v60
	v_fma_f32 v60, v90, v98, v60
	v_fma_f32 v60, v91, v99, v60
	v_add_f32_e32 v20, v20, v60
	s_waitcnt lgkmcnt(7)
	v_mul_f32_e32 v60, v89, v101
	v_fma_f32 v60, v88, v100, v60
	v_fma_f32 v60, v90, v102, v60
	v_fma_f32 v60, v91, v103, v60
	v_add_f32_e32 v21, v21, v60
	s_waitcnt lgkmcnt(6)
	v_mul_f32_e32 v60, v89, v105
	v_fma_f32 v60, v88, v104, v60
	v_fma_f32 v60, v90, v106, v60
	v_fma_f32 v60, v91, v107, v60
	v_add_f32_e32 v22, v22, v60
	s_waitcnt lgkmcnt(5)
	v_mul_f32_e32 v60, v89, v109
	v_fma_f32 v60, v88, v108, v60
	v_fma_f32 v60, v90, v110, v60
	v_fma_f32 v60, v91, v111, v60
	v_add_f32_e32 v23, v23, v60
	s_waitcnt lgkmcnt(4)
	v_mul_f32_e32 v60, v89, v113
	v_fma_f32 v60, v88, v112, v60
	v_fma_f32 v60, v90, v114, v60
	v_fma_f32 v60, v91, v115, v60
	v_add_f32_e32 v24, v24, v60
	s_waitcnt lgkmcnt(3)
	v_mul_f32_e32 v60, v89, v117
	v_fma_f32 v60, v88, v116, v60
	v_fma_f32 v60, v90, v118, v60
	v_fma_f32 v60, v91, v119, v60
	v_add_f32_e32 v25, v25, v60
	s_waitcnt lgkmcnt(2)
	v_mul_f32_e32 v60, v89, v121
	v_fma_f32 v60, v88, v120, v60
	v_fma_f32 v60, v90, v122, v60
	v_fma_f32 v60, v91, v123, v60
	v_add_f32_e32 v26, v26, v60
	s_waitcnt lgkmcnt(1)
	v_mul_f32_e32 v60, v89, v125
	v_fma_f32 v60, v88, v124, v60
	v_fma_f32 v60, v90, v126, v60
	v_fma_f32 v60, v91, v127, v60
	v_add_f32_e32 v27, v27, v60
	s_waitcnt lgkmcnt(0)
	v_mul_f32_e32 v60, v88, v128
	v_mul_f32_e32 v61, v89, v129
	v_add_f32_e32 v60, v60, v61
	v_mul_f32_e32 v61, v90, v130
	v_add_f32_e32 v60, v61, v60
	v_mul_f32_e32 v61, v91, v131
	v_add_f32_e32 v60, v61, v60
	v_add_f32_e32 v30, v30, v60
	ds_read_b128 v[96:99], v41 offset:48
	ds_read_b128 v[100:103], v41 offset:4144
	ds_read_b128 v[104:107], v41 offset:8240
	ds_read_b128 v[108:111], v41 offset:12336
	ds_read_b128 v[112:115], v41 offset:16432
	ds_read_b128 v[116:119], v41 offset:20528
	ds_read_b128 v[120:123], v41 offset:24624
	ds_read_b128 v[124:127], v41 offset:28720
	ds_read_b128 v[128:131], v41 offset:32816
	s_waitcnt lgkmcnt(8)
	v_mul_f32_e32 v60, v93, v97
	v_fma_f32 v60, v92, v96, v60
	v_fma_f32 v60, v94, v98, v60
	v_fma_f32 v60, v95, v99, v60
	v_add_f32_e32 v20, v20, v60
	s_waitcnt lgkmcnt(7)
	v_mul_f32_e32 v60, v93, v101
	v_fma_f32 v60, v92, v100, v60
	v_fma_f32 v60, v94, v102, v60
	v_fma_f32 v60, v95, v103, v60
	v_add_f32_e32 v21, v21, v60
	s_waitcnt lgkmcnt(6)
	v_mul_f32_e32 v60, v93, v105
	v_fma_f32 v60, v92, v104, v60
	v_fma_f32 v60, v94, v106, v60
	v_fma_f32 v60, v95, v107, v60
	v_add_f32_e32 v22, v22, v60
	s_waitcnt lgkmcnt(5)
	v_mul_f32_e32 v60, v93, v109
	v_fma_f32 v60, v92, v108, v60
	v_fma_f32 v60, v94, v110, v60
	v_fma_f32 v60, v95, v111, v60
	v_add_f32_e32 v23, v23, v60
	s_waitcnt lgkmcnt(4)
	v_mul_f32_e32 v60, v93, v113
	v_fma_f32 v60, v92, v112, v60
	v_fma_f32 v60, v94, v114, v60
	v_fma_f32 v60, v95, v115, v60
	v_add_f32_e32 v24, v24, v60
	s_waitcnt lgkmcnt(3)
	v_mul_f32_e32 v60, v93, v117
	v_fma_f32 v60, v92, v116, v60
	v_fma_f32 v60, v94, v118, v60
	v_fma_f32 v60, v95, v119, v60
	v_add_f32_e32 v25, v25, v60
	s_waitcnt lgkmcnt(2)
	v_mul_f32_e32 v60, v93, v121
	v_fma_f32 v60, v92, v120, v60
	v_fma_f32 v60, v94, v122, v60
	v_fma_f32 v60, v95, v123, v60
	v_add_f32_e32 v26, v26, v60
	s_waitcnt lgkmcnt(1)
	v_mul_f32_e32 v60, v93, v125
	v_fma_f32 v60, v92, v124, v60
	v_fma_f32 v60, v94, v126, v60
	v_fma_f32 v60, v95, v127, v60
	v_add_f32_e32 v27, v27, v60
	s_waitcnt lgkmcnt(0)
	v_mul_f32_e32 v60, v92, v128
	v_mul_f32_e32 v61, v93, v129
	v_add_f32_e32 v60, v60, v61
	v_mul_f32_e32 v61, v94, v130
	v_add_f32_e32 v60, v61, v60
	v_mul_f32_e32 v61, v95, v131
	v_add_f32_e32 v60, v61, v60
	v_add_f32_e32 v30, v30, v60
	v_add_u32_e32 v41, 64, v41
	ds_write2st64_b32 v40, v20, v21 offset0:144 offset1:145
	ds_write2st64_b32 v40, v22, v23 offset0:146 offset1:147
	ds_write2st64_b32 v40, v24, v25 offset0:148 offset1:149
	ds_write2st64_b32 v40, v26, v27 offset0:150 offset1:151
	ds_write_b32 v40, v30 offset:38912
	s_waitcnt lgkmcnt(0)
	s_barrier
	s_and_saveexec_b64 s[8:9], s[4:5]
	s_cbranch_execz .LBB0_1325
	v_readlane_b32 s2, v254, 25
	v_readlane_b32 s3, v254, 26
	s_load_dwordx2 s[2:3], s[2:3], 0x60
	s_mul_i32 s13, s1, 0x6000
	s_mul_hi_i32 s12, s1, 0x6000
	s_mul_hi_i32 s11, s1, 9
	s_mul_i32 s10, s1, 9
	s_waitcnt lgkmcnt(0)
	s_add_u32 s1, s2, s13
	s_addc_u32 s3, s3, s12
	s_add_u32 s2, s1, s6
	s_addc_u32 s3, s3, s7
	v_lshl_add_u64 v[2:3], s[2:3], 0, v[0:1]
	v_lshl_add_u64 v[4:5], v[14:15], 0, s[6:7]
	s_mov_b64 s[6:7], 0
	v_mov_b32_e32 v6, v31
